# lever 7 (cross-lane ops instead of LDS round trips): mixer A row-max / row-sum half-wave exchange by v_permlane32_swap instead of ds_bpermute
# baseline (speedup 1.0000x reference)
; #define LAS __attribute__((address_space(3)))
; #define MFMA32(a, b, c) __builtin_amdgcn_mfma_f32_32x32x16_bf16((a), (b), (c), 0, 0, 0)
; __device__ __forceinline__ s16x4 lds_tr(const LAS unsigned char* p) { return __builtin_bit_cast(s16x4, __builtin_amdgcn_ds_read_tr16_b64_v4i16((LAS v4i16_t*)p)); }
; __device__ __forceinline__ void attnA_unit(LAS unsigned char* lds, const Args& A, int unit) {
;     ...
;                 float mx = fmaxf(mxp[0], mxp[1]);
;                 mx = fmaxf(mx, __shfl_xor(mx, 32));
;                 float lsp[2] = {0.f, 0.f};
; #pragma unroll
;                 for (int kt = 0; kt < 5; ++kt)
; #pragma unroll
;                     for (int i = 0; i < 16; ++i) { const float p = __builtin_amdgcn_exp2f(S[kt][i] - mx); S[kt][i] = p; lsp[i & 1] += p; }
;                 float ls = lsp[0] + lsp[1];
;                 ls += __shfl_xor(ls, 32);
;                 f32x16 o0, o1;
; #pragma unroll
;                 for (int i = 0; i < 16; ++i) { o0[i] = 0.f; o1[i] = 0.f; }
;                 const LAS unsigned char* vr0 = vt_l + (rb + 4 * hh + ((lane & 15) >> 2)) * AST + 32 * ((lane >> 4) & 1) + 8 * (lane & 3);
; #pragma unroll
;                 for (int kt = 0; kt < 5; ++kt)
; #pragma unroll
;                     for (int ks = 0; ks < 2; ++ks) {
;                         const bf16x8 pf = pack_frag(S[kt], ks);
;                         const LAS unsigned char* vr = vr0 + (32 * kt + 16 * ks) * AST;
;                         const s16x4 a0 = lds_tr(vr), a1 = lds_tr(vr + 8 * AST), c0 = lds_tr(vr + 64), c1 = lds_tr(vr + 8 * AST + 64);
;                         o0 = MFMA32(__builtin_shufflevector(a0, a1, 0, 1, 2, 3, 4, 5, 6, 7), pf, o0);
;                         o1 = MFMA32(__builtin_shufflevector(c0, c1, 0, 1, 2, 3, 4, 5, 6, 7), pf, o1);
.LmixA_join:
	v_lshlrev_b32_e32 v32, v206, v164
	v_mov_b32_e32 v1, v0
	v_mov_b32_e32 v253, v0
	s_nop 1
	v_permlane32_swap_b32_e32 v1, v253
	s_nop 0
	v_max_f32_e32 v229, v1, v253
	v_mul_f32_e32 v229, 0x3e38aa3b, v229
	v_mov_b32_e32 v252, 0x3e38aa3b
	v_fma_f32 v10, v76, v252, -v229
	v_exp_f32_e32 v172, v10
	v_fma_f32 v10, v77, v252, -v229
	v_exp_f32_e32 v173, v10
	v_fma_f32 v10, v78, v252, -v229
	v_exp_f32_e32 v174, v10
	v_fma_f32 v10, v79, v252, -v229
	v_exp_f32_e32 v175, v10
	v_fma_f32 v10, v48, v252, -v229
	v_fma_f32 v8, v72, v252, -v229
	v_exp_f32_e32 v72, v10
	v_fma_f32 v10, v49, v252, -v229
	v_exp_f32_e32 v166, v8
	v_fma_f32 v8, v73, v252, -v229
	v_exp_f32_e32 v73, v10
	v_fma_f32 v10, v50, v252, -v229
	v_exp_f32_e32 v167, v8
	v_fma_f32 v8, v74, v252, -v229
	v_exp_f32_e32 v74, v10
	v_fma_f32 v10, v51, v252, -v229
	v_exp_f32_e32 v75, v10
	v_fma_f32 v10, v52, v252, -v229
	v_exp_f32_e32 v76, v10
	v_fma_f32 v10, v53, v252, -v229
	v_exp_f32_e32 v77, v10
	v_fma_f32 v10, v54, v252, -v229
	v_exp_f32_e32 v78, v10
	v_fma_f32 v10, v55, v252, -v229
	v_exp_f32_e32 v79, v10
	v_fma_f32 v10, v56, v252, -v229
	v_exp_f32_e32 v62, v10
	v_fma_f32 v10, v57, v252, -v229
	v_exp_f32_e32 v63, v10
	v_fma_f32 v10, v58, v252, -v229
	v_fma_f32 v2, v66, v252, -v229
	v_exp_f32_e32 v66, v10
	v_fma_f32 v10, v59, v252, -v229
	v_fma_f32 v0, v64, v252, -v229
	v_fma_f32 v1, v65, v252, -v229
	v_fma_f32 v3, v67, v252, -v229
	v_exp_f32_e32 v67, v10
	v_fma_f32 v10, v60, v252, -v229
	v_exp_f32_e32 v0, v0
	v_exp_f32_e32 v1, v1
	v_fma_f32 v4, v68, v252, -v229
	v_exp_f32_e32 v68, v10
	v_fma_f32 v10, v61, v252, -v229
	v_exp_f32_e32 v2, v2
	v_exp_f32_e32 v3, v3
	v_fma_f32 v5, v69, v252, -v229
	v_exp_f32_e32 v69, v10
	v_fma_f32 v10, v169, v252, -v229
	v_exp_f32_e32 v4, v4
	v_exp_f32_e32 v5, v5
	v_fma_f32 v6, v70, v252, -v229
	v_fma_f32 v7, v71, v252, -v229
	v_exp_f32_e32 v70, v10
	v_fma_f32 v10, v208, v252, -v229
	v_exp_f32_e32 v6, v6
	v_exp_f32_e32 v7, v7
	v_exp_f32_e32 v170, v8
	v_fma_f32 v8, v168, v252, -v229
	v_exp_f32_e32 v71, v10
	v_fma_f32 v10, v209, v252, -v229
	v_exp_f32_e32 v171, v8
	v_pk_add_f32 v[8:9], v[0:1], 0 op_sel_hi:[1,0]
	v_exp_f32_e32 v54, v10
	v_fma_f32 v10, v33, v252, -v229
	v_pk_add_f32 v[8:9], v[2:3], v[8:9]
	v_exp_f32_e32 v55, v10
	v_fma_f32 v10, v34, v252, -v229
	v_pk_add_f32 v[8:9], v[4:5], v[8:9]
	v_exp_f32_e32 v58, v10
	v_fma_f32 v10, v35, v252, -v229
	v_pk_add_f32 v[8:9], v[6:7], v[8:9]
	v_exp_f32_e32 v59, v10
	v_fma_f32 v10, v36, v252, -v229
	v_pk_add_f32 v[8:9], v[166:167], v[8:9]
	v_exp_f32_e32 v60, v10
	v_fma_f32 v10, v37, v252, -v229
	v_pk_add_f32 v[8:9], v[170:171], v[8:9]
	v_exp_f32_e32 v61, v10
	v_fma_f32 v10, v38, v252, -v229
	v_pk_add_f32 v[8:9], v[172:173], v[8:9]
	v_exp_f32_e32 v64, v10
	v_fma_f32 v10, v39, v252, -v229
	v_pk_add_f32 v[8:9], v[174:175], v[8:9]
	v_exp_f32_e32 v65, v10
	v_fma_f32 v10, v40, v252, -v229
	v_pk_add_f32 v[8:9], v[72:73], v[8:9]
	v_exp_f32_e32 v48, v10
	v_fma_f32 v10, v41, v252, -v229
	v_pk_add_f32 v[8:9], v[74:75], v[8:9]
	v_exp_f32_e32 v49, v10
	v_fma_f32 v10, v42, v252, -v229
	v_pk_add_f32 v[8:9], v[76:77], v[8:9]
	v_exp_f32_e32 v50, v10
	v_fma_f32 v10, v43, v252, -v229
	v_pk_add_f32 v[8:9], v[78:79], v[8:9]
	v_exp_f32_e32 v51, v10
	v_fma_f32 v10, v44, v252, -v229
	v_pk_add_f32 v[8:9], v[62:63], v[8:9]
	v_exp_f32_e32 v52, v10
	v_fma_f32 v10, v45, v252, -v229
	v_pk_add_f32 v[8:9], v[66:67], v[8:9]
	v_exp_f32_e32 v53, v10
	v_fma_f32 v10, v46, v252, -v229
	v_pk_add_f32 v[8:9], v[68:69], v[8:9]
	v_exp_f32_e32 v56, v10
	v_fma_f32 v10, v47, v252, -v229
	v_pk_add_f32 v[8:9], v[70:71], v[8:9]
	v_exp_f32_e32 v57, v10
	v_fma_f32 v10, v16, v252, -v229
	v_pk_add_f32 v[8:9], v[54:55], v[8:9]
	v_exp_f32_e32 v38, v10
	v_fma_f32 v10, v17, v252, -v229
	v_exp_f32_e32 v39, v10
	v_fma_f32 v10, v18, v252, -v229
	v_pk_add_f32 v[8:9], v[58:59], v[8:9]
	v_exp_f32_e32 v40, v10
	v_fma_f32 v10, v19, v252, -v229
	v_pk_add_f32 v[8:9], v[60:61], v[8:9]
	v_exp_f32_e32 v41, v10
	v_fma_f32 v10, v20, v252, -v229
	v_pk_add_f32 v[8:9], v[64:65], v[8:9]
	v_exp_f32_e32 v42, v10
	v_fma_f32 v10, v21, v252, -v229
	v_pk_add_f32 v[8:9], v[48:49], v[8:9]
	v_exp_f32_e32 v43, v10
	v_fma_f32 v10, v22, v252, -v229
	v_pk_add_f32 v[8:9], v[50:51], v[8:9]
	v_exp_f32_e32 v44, v10
	v_fma_f32 v10, v23, v252, -v229
	v_pk_add_f32 v[8:9], v[52:53], v[8:9]
	v_exp_f32_e32 v45, v10
	v_pk_add_f32 v[8:9], v[56:57], v[8:9]
	v_fma_f32 v12, v27, v252, -v229
	v_pk_add_f32 v[8:9], v[38:39], v[8:9]
	v_cvt_pk_bf16_f32 v16, v0, v1
	v_pk_add_f32 v[8:9], v[40:41], v[8:9]
	v_cvt_pk_bf16_f32 v17, v2, v3
	v_pk_add_f32 v[8:9], v[42:43], v[8:9]
	v_cvt_pk_bf16_f32 v18, v4, v5
	v_pk_add_f32 v[46:47], v[44:45], v[8:9]
	v_fma_f32 v8, v24, v252, -v229
	v_exp_f32_e32 v34, v8
	v_fma_f32 v8, v25, v252, -v229
	v_exp_f32_e32 v35, v8
	v_fma_f32 v8, v26, v252, -v229
	v_exp_f32_e32 v36, v8
	v_add_u32_e32 v8, v180, v163
	v_mad_u64_u32 v[246:247], s[22:23], v8, s88, v[152:153]
	ds_read_b64_tr_b16 v[8:9], v246 offset:59392
	ds_read_b64_tr_b16 v[10:11], v246 offset:60544
	v_cvt_pk_bf16_f32 v19, v6, v7
	v_exp_f32_e32 v37, v12
	v_fma_f32 v24, v28, v252, -v229
	ds_read_b64_tr_b16 v[20:21], v246 offset:59456
	ds_read_b64_tr_b16 v[22:23], v246 offset:60608
	s_waitcnt lgkmcnt(2)
	v_mfma_f32_32x32x16_bf16 v[0:15], v[8:11], v[16:19], 0
	v_exp_f32_e32 v164, v24
	v_fma_f32 v24, v29, v252, -v229
	ds_read_b64_tr_b16 v[208:209], v246 offset:61696
	ds_read_b64_tr_b16 v[210:211], v246 offset:62848
	v_exp_f32_e32 v165, v24
	v_fma_f32 v24, v30, v252, -v229
	v_exp_f32_e32 v168, v24
	v_cvt_pk_bf16_f32 v242, v166, v167
	s_waitcnt lgkmcnt(2)
; #define LAS __attribute__((address_space(3)))
; #define MFMA32(a, b, c) __builtin_amdgcn_mfma_f32_32x32x16_bf16((a), (b), (c), 0, 0, 0)
; __device__ __forceinline__ s16x4 lds_tr(const LAS unsigned char* p) { return __builtin_bit_cast(s16x4, __builtin_amdgcn_ds_read_tr16_b64_v4i16((LAS v4i16_t*)p)); }
; __device__ __forceinline__ void attnA_unit(LAS unsigned char* lds, const Args& A, int unit) {
;     ...
;                 float lsp[2] = {0.f, 0.f};
; #pragma unroll
;                 for (int kt = 0; kt < 5; ++kt)
; #pragma unroll
;                     for (int i = 0; i < 16; ++i) { const float p = __builtin_amdgcn_exp2f(S[kt][i] - mx); S[kt][i] = p; lsp[i & 1] += p; }
;                 float ls = lsp[0] + lsp[1];
;                 ls += __shfl_xor(ls, 32);
;                 f32x16 o0, o1;
; #pragma unroll
;                 for (int i = 0; i < 16; ++i) { o0[i] = 0.f; o1[i] = 0.f; }
;                 const LAS unsigned char* vr0 = vt_l + (rb + 4 * hh + ((lane & 15) >> 2)) * AST + 32 * ((lane >> 4) & 1) + 8 * (lane & 3);
; #pragma unroll
;                 for (int kt = 0; kt < 5; ++kt)
; #pragma unroll
;                     for (int ks = 0; ks < 2; ++ks) {
;                         const bf16x8 pf = pack_frag(S[kt], ks);
;                         const LAS unsigned char* vr = vr0 + (32 * kt + 16 * ks) * AST;
;                         const s16x4 a0 = lds_tr(vr), a1 = lds_tr(vr + 8 * AST), c0 = lds_tr(vr + 64), c1 = lds_tr(vr + 8 * AST + 64);
;                         o0 = MFMA32(__builtin_shufflevector(a0, a1, 0, 1, 2, 3, 4, 5, 6, 7), pf, o0);
;                         o1 = MFMA32(__builtin_shufflevector(c0, c1, 0, 1, 2, 3, 4, 5, 6, 7), pf, o1);
	v_mfma_f32_32x32x16_bf16 v[16:31], v[20:23], v[16:19], 0
	v_cvt_pk_bf16_f32 v243, v170, v171
	v_cvt_pk_bf16_f32 v244, v172, v173
	v_cvt_pk_bf16_f32 v245, v174, v175
	ds_read_b64_tr_b16 v[170:171], v246 offset:61760
	ds_read_b64_tr_b16 v[172:173], v246 offset:62912
	v_add_u32_e32 v163, 0xe800, v246
	v_cvt_pk_bf16_f32 v48, v48, v49
	v_cvt_pk_bf16_f32 v49, v50, v51
	s_waitcnt lgkmcnt(2)
	v_mfma_f32_32x32x16_bf16 v[0:15], v[208:211], v[242:245], v[0:15]
	ds_read_b64_tr_b16 v[208:209], v246 offset:64000
	ds_read_b64_tr_b16 v[210:211], v246 offset:65152
	v_cvt_pk_bf16_f32 v50, v52, v53
	v_cvt_pk_bf16_f32 v51, v56, v57
	v_fma_f32 v33, v224, v252, -v229
	v_exp_f32_e32 v169, v33
	v_fma_f32 v33, v223, v252, -v229
	v_cvt_pk_bf16_f32 v38, v38, v39
	s_waitcnt lgkmcnt(2)
	v_mfma_f32_32x32x16_bf16 v[16:31], v[170:173], v[242:245], v[16:31]
	v_cvt_pk_bf16_f32 v170, v72, v73
	v_cvt_pk_bf16_f32 v171, v74, v75
	v_cvt_pk_bf16_f32 v172, v76, v77
	v_cvt_pk_bf16_f32 v173, v78, v79
	ds_read_b64_tr_b16 v[74:75], v246 offset:64064
	ds_read_b64_tr_b16 v[76:77], v246 offset:65216
	v_cvt_pk_bf16_f32 v78, v68, v69
	v_cvt_pk_bf16_f32 v79, v70, v71
	s_waitcnt lgkmcnt(2)
	v_mfma_f32_32x32x16_bf16 v[0:15], v[208:211], v[170:173], v[0:15]
	ds_read_b64_tr_b16 v[208:209], v163 offset:6912
	ds_read_b64_tr_b16 v[210:211], v163 offset:8064
	v_cvt_pk_bf16_f32 v39, v40, v41
	v_cvt_pk_bf16_f32 v40, v42, v43
	v_cvt_pk_bf16_f32 v41, v44, v45
	v_exp_f32_e32 v166, v33
	v_fma_f32 v33, v226, v252, -v229
	v_exp_f32_e32 v167, v33
	s_waitcnt lgkmcnt(2)
	v_mfma_f32_32x32x16_bf16 v[16:31], v[74:77], v[170:173], v[16:31]
	v_cvt_pk_bf16_f32 v76, v62, v63
	v_cvt_pk_bf16_f32 v77, v66, v67
	ds_read_b64_tr_b16 v[66:67], v163 offset:6976
	ds_read_b64_tr_b16 v[68:69], v163 offset:8128
	ds_read_b64_tr_b16 v[170:171], v163 offset:9216
	ds_read_b64_tr_b16 v[172:173], v163 offset:10368
	v_fma_f32 v33, v225, v252, -v229
	v_exp_f32_e32 v72, v33
	v_fma_f32 v33, v227, v252, -v229
	s_waitcnt lgkmcnt(4)
	v_mfma_f32_32x32x16_bf16 v[0:15], v[208:211], v[76:79], v[0:15]
	v_exp_f32_e32 v73, v33
	v_fma_f32 v33, v228, v252, -v229
	v_exp_f32_e32 v74, v33
	v_fma_f32 v33, v230, v252, -v229
	v_exp_f32_e32 v75, v33
	v_fma_f32 v33, v232, v252, -v229
	v_exp_f32_e32 v62, v33
	s_waitcnt lgkmcnt(2)
	v_mfma_f32_32x32x16_bf16 v[16:31], v[66:69], v[76:79], v[16:31]
	v_cvt_pk_bf16_f32 v66, v54, v55
	v_cvt_pk_bf16_f32 v67, v58, v59
	v_cvt_pk_bf16_f32 v68, v60, v61
	v_cvt_pk_bf16_f32 v69, v64, v65
	ds_read_b64_tr_b16 v[58:59], v163 offset:9280
	ds_read_b64_tr_b16 v[60:61], v163 offset:10432
	ds_read_b64_tr_b16 v[76:77], v163 offset:11520
	ds_read_b64_tr_b16 v[78:79], v163 offset:12672
	v_fma_f32 v33, v233, v252, -v229
	s_waitcnt lgkmcnt(4)
	v_mfma_f32_32x32x16_bf16 v[0:15], v[170:173], v[66:69], v[0:15]
	v_exp_f32_e32 v63, v33
	v_fma_f32 v33, v231, v252, -v229
	v_exp_f32_e32 v54, v33
	v_fma_f32 v33, v234, v252, -v229
	v_exp_f32_e32 v55, v33
	v_fma_f32 v33, v235, v252, -v229
	s_waitcnt lgkmcnt(2)
	v_mfma_f32_32x32x16_bf16 v[16:31], v[58:61], v[66:69], v[16:31]
	ds_read_b64_tr_b16 v[56:57], v163 offset:11584
	ds_read_b64_tr_b16 v[58:59], v163 offset:12736
	ds_read_b64_tr_b16 v[64:65], v163 offset:13824
	ds_read_b64_tr_b16 v[66:67], v163 offset:14976
	ds_read_b64_tr_b16 v[42:43], v163 offset:13888
	ds_read_b64_tr_b16 v[44:45], v163 offset:15040
	v_exp_f32_e32 v60, v33
	v_fma_f32 v33, v236, v252, -v229
	v_exp_f32_e32 v61, v33
	v_fma_f32 v33, v237, v252, -v229
	s_waitcnt lgkmcnt(6)
	v_mfma_f32_32x32x16_bf16 v[0:15], v[76:79], v[48:51], v[0:15]
	v_exp_f32_e32 v52, v33
	v_fma_f32 v33, v240, v252, -v229
	v_exp_f32_e32 v53, v33
	v_fma_f32 v33, v239, v252, -v229
	s_waitcnt lgkmcnt(4)
	v_mfma_f32_32x32x16_bf16 v[16:31], v[56:59], v[48:51], v[16:31]
	v_add_f32_e64 v56, v34, v46
	v_add_f32_e64 v57, v35, v47
	ds_read_b64_tr_b16 v[46:47], v163 offset:16128
	ds_read_b64_tr_b16 v[48:49], v163 offset:17280
	v_cvt_pk_bf16_f32 v34, v34, v35
	v_cvt_pk_bf16_f32 v35, v36, v37
	v_exp_f32_e32 v50, v33
	v_fma_f32 v33, v241, v252, -v229
	v_exp_f32_e32 v51, v33
	s_waitcnt lgkmcnt(4)
	v_mfma_f32_32x32x16_bf16 v[0:15], v[64:67], v[38:41], v[0:15]
	s_waitcnt lgkmcnt(2)
	v_mfma_f32_32x32x16_bf16 v[16:31], v[42:45], v[38:41], v[16:31]
	v_add_f32_e64 v42, v36, v56
	v_add_f32_e64 v43, v37, v57
	v_cvt_pk_bf16_f32 v36, v164, v165
	v_cvt_pk_bf16_f32 v37, v168, v169
	v_add_f32_e64 v42, v164, v42
	v_add_f32_e64 v43, v165, v43
	ds_read_b64_tr_b16 v[38:39], v163 offset:16192
	ds_read_b64_tr_b16 v[40:41], v163 offset:17344
	v_pk_add_f32 v[42:43], v[168:169], v[42:43]
	s_waitcnt lgkmcnt(2)
; #define LAS __attribute__((address_space(3)))
; #define MFMA32(a, b, c) __builtin_amdgcn_mfma_f32_32x32x16_bf16((a), (b), (c), 0, 0, 0)
; __device__ __forceinline__ unsigned cvtpk(float lo, float hi) { f32x2_t v = {lo, hi}; bf16x2_t b = __builtin_convertvector(v, bf16x2_t); return __builtin_bit_cast(unsigned, b); }
; __device__ __forceinline__ s16x4 lds_tr(const LAS unsigned char* p) { return __builtin_bit_cast(s16x4, __builtin_amdgcn_ds_read_tr16_b64_v4i16((LAS v4i16_t*)p)); }
; __device__ __forceinline__ void attnA_unit(LAS unsigned char* lds, const Args& A, int unit) {
;     ...
;                 float ls = lsp[0] + lsp[1];
;                 ls += __shfl_xor(ls, 32);
;                 f32x16 o0, o1;
; #pragma unroll
;                 for (int i = 0; i < 16; ++i) { o0[i] = 0.f; o1[i] = 0.f; }
;                 const LAS unsigned char* vr0 = vt_l + (rb + 4 * hh + ((lane & 15) >> 2)) * AST + 32 * ((lane >> 4) & 1) + 8 * (lane & 3);
; #pragma unroll
;                 for (int kt = 0; kt < 5; ++kt)
; #pragma unroll
;                     for (int ks = 0; ks < 2; ++ks) {
;                         const bf16x8 pf = pack_frag(S[kt], ks);
;                         const LAS unsigned char* vr = vr0 + (32 * kt + 16 * ks) * AST;
;                         const s16x4 a0 = lds_tr(vr), a1 = lds_tr(vr + 8 * AST), c0 = lds_tr(vr + 64), c1 = lds_tr(vr + 8 * AST + 64);
;                         o0 = MFMA32(__builtin_shufflevector(a0, a1, 0, 1, 2, 3, 4, 5, 6, 7), pf, o0);
;                         o1 = MFMA32(__builtin_shufflevector(c0, c1, 0, 1, 2, 3, 4, 5, 6, 7), pf, o1);
;                     }
;                 const float inv = 1.0f / ls;
;                 bf16* orow = Qrow + 4 * hh;
; #pragma unroll
;                 for (int g4 = 0; g4 < 4; ++g4) {
;                     u32x2 w; w.x = cvtpk(o0[4 * g4] * inv, o0[4 * g4 + 1] * inv); w.y = cvtpk(o0[4 * g4 + 2] * inv, o0[4 * g4 + 3] * inv); *(u32x2*)(orow + 8 * g4) = w;
;                     u32x2 z; z.x = cvtpk(o1[4 * g4] * inv, o1[4 * g4 + 1] * inv); z.y = cvtpk(o1[4 * g4 + 2] * inv, o1[4 * g4 + 3] * inv); *(u32x2*)(orow + 32 + 8 * g4) = z;
;                 }
;                 if (hh == 0) LSE[(size_t)((g * 4 + b) * 8 + h) * 8192 + pbase + i0 + ql] = mx + __builtin_amdgcn_logf(ls);
	v_mfma_f32_32x32x16_bf16 v[0:15], v[46:49], v[34:37], v[0:15]
	v_add_f32_e64 v42, v166, v42
	v_add_f32_e64 v43, v167, v43
	v_add_f32_e64 v42, v72, v42
	v_add_f32_e64 v43, v73, v43
	v_add_f32_e64 v46, v74, v42
	v_add_f32_e64 v47, v75, v43
	ds_read_b64_tr_b16 v[42:43], v163 offset:18432
	ds_read_b64_tr_b16 v[44:45], v163 offset:19584
	v_pk_add_f32 v[46:47], v[62:63], v[46:47]
	s_waitcnt lgkmcnt(2)
	v_mfma_f32_32x32x16_bf16 v[16:31], v[38:41], v[34:37], v[16:31]
	v_cvt_pk_bf16_f32 v34, v166, v167
	v_cvt_pk_bf16_f32 v35, v72, v73
	v_cvt_pk_bf16_f32 v36, v74, v75
	v_cvt_pk_bf16_f32 v37, v62, v63
	ds_read_b64_tr_b16 v[38:39], v163 offset:18496
	ds_read_b64_tr_b16 v[40:41], v163 offset:19648
	s_waitcnt lgkmcnt(2)
	v_mfma_f32_32x32x16_bf16 v[0:15], v[42:45], v[34:37], v[0:15]
	v_add_f32_e64 v42, v54, v46
	v_add_f32_e64 v43, v55, v47
	v_add_f32_e64 v42, v60, v42
	v_add_f32_e64 v43, v61, v43
	v_add_f32_e64 v42, v52, v42
	v_add_f32_e64 v43, v53, v43
	v_pk_add_f32 v[42:43], v[50:51], v[42:43]
	s_waitcnt lgkmcnt(0)
	v_mfma_f32_32x32x16_bf16 v[16:31], v[38:41], v[34:37], v[16:31]
	v_add_f32_e32 v33, v42, v43
	ds_read_b64_tr_b16 v[42:43], v163 offset:20736
	ds_read_b64_tr_b16 v[44:45], v163 offset:21888
	ds_read_b64_tr_b16 v[46:47], v163 offset:20800
	ds_read_b64_tr_b16 v[48:49], v163 offset:21952
	v_cvt_pk_bf16_f32 v36, v54, v55
	v_cvt_pk_bf16_f32 v37, v60, v61
	s_waitcnt lgkmcnt(4)
	v_mov_b32_e32 v34, v33
	v_mov_b32_e32 v253, v33
	s_nop 1
	v_permlane32_swap_b32_e32 v34, v253
	s_nop 0
	v_add_f32_e32 v34, v34, v253
	v_div_scale_f32 v33, s[22:23], v34, v34, 1.0
	v_rcp_f32_e32 v35, v33
	v_cvt_pk_bf16_f32 v38, v52, v53
	v_cvt_pk_bf16_f32 v39, v50, v51
	v_add3_u32 v40, v162, v144, v32
	v_ashrrev_i32_e32 v41, 31, v40
	s_waitcnt lgkmcnt(2)
	v_mfma_f32_32x32x16_bf16 v[0:15], v[42:45], v[36:39], v[0:15]
	v_lshlrev_b64 v[40:41], 7, v[40:41]
	s_waitcnt lgkmcnt(0)
	v_mfma_f32_32x32x16_bf16 v[16:31], v[46:49], v[36:39], v[16:31]
	v_fma_f32 v36, -v33, v35, 1.0
	v_fmac_f32_e32 v35, v36, v35
	v_div_scale_f32 v36, vcc, 1.0, v34, 1.0
	v_mul_f32_e32 v37, v36, v35
	v_fma_f32 v38, -v33, v37, v36
	v_fmac_f32_e32 v37, v38, v35
	v_fma_f32 v33, -v33, v37, v36
	v_div_fmas_f32 v33, v33, v35, v37
	v_div_fixup_f32 v36, v33, v34, 1.0
	v_pk_mul_f32 v[0:1], v[36:37], v[0:1] op_sel_hi:[0,1]
	v_pk_mul_f32 v[2:3], v[36:37], v[2:3] op_sel_hi:[0,1]
	v_lshl_add_u64 v[38:39], v[160:161], 0, v[40:41]
	v_cvt_pk_bf16_f32 v0, v0, v1
	v_cvt_pk_bf16_f32 v1, v2, v3
	global_store_dwordx2 v[38:39], v[0:1], off
	v_pk_mul_f32 v[0:1], v[36:37], v[16:17] op_sel_hi:[0,1]
	v_pk_mul_f32 v[2:3], v[36:37], v[18:19] op_sel_hi:[0,1]
	v_cvt_pk_bf16_f32 v0, v0, v1
	v_cvt_pk_bf16_f32 v1, v2, v3
	global_store_dwordx2 v[38:39], v[0:1], off offset:64
	v_pk_mul_f32 v[0:1], v[36:37], v[4:5] op_sel_hi:[0,1]
	v_pk_mul_f32 v[2:3], v[36:37], v[6:7] op_sel_hi:[0,1]
	v_cvt_pk_bf16_f32 v0, v0, v1
	v_cvt_pk_bf16_f32 v1, v2, v3
	global_store_dwordx2 v[38:39], v[0:1], off offset:16
	v_pk_mul_f32 v[0:1], v[36:37], v[20:21] op_sel_hi:[0,1]
	v_pk_mul_f32 v[2:3], v[36:37], v[22:23] op_sel_hi:[0,1]
	v_cvt_pk_bf16_f32 v0, v0, v1
	v_cvt_pk_bf16_f32 v1, v2, v3
	global_store_dwordx2 v[38:39], v[0:1], off offset:80
	v_pk_mul_f32 v[0:1], v[36:37], v[8:9] op_sel_hi:[0,1]
	v_pk_mul_f32 v[2:3], v[36:37], v[10:11] op_sel_hi:[0,1]
	v_cvt_pk_bf16_f32 v0, v0, v1
	v_cvt_pk_bf16_f32 v1, v2, v3
	global_store_dwordx2 v[38:39], v[0:1], off offset:32
	v_pk_mul_f32 v[0:1], v[36:37], v[24:25] op_sel_hi:[0,1]
	v_pk_mul_f32 v[2:3], v[36:37], v[26:27] op_sel_hi:[0,1]
	v_cvt_pk_bf16_f32 v0, v0, v1
	v_cvt_pk_bf16_f32 v1, v2, v3
	global_store_dwordx2 v[38:39], v[0:1], off offset:96
	v_pk_mul_f32 v[0:1], v[36:37], v[12:13] op_sel_hi:[0,1]
	v_pk_mul_f32 v[2:3], v[36:37], v[14:15] op_sel_hi:[0,1]
	v_cvt_pk_bf16_f32 v0, v0, v1
	v_cvt_pk_bf16_f32 v1, v2, v3
	global_store_dwordx2 v[38:39], v[0:1], off offset:48
	v_pk_mul_f32 v[0:1], v[36:37], v[28:29] op_sel_hi:[0,1]
	v_pk_mul_f32 v[2:3], v[36:37], v[30:31] op_sel_hi:[0,1]
	v_cvt_pk_bf16_f32 v0, v0, v1
	v_cvt_pk_bf16_f32 v1, v2, v3
	global_store_dwordx2 v[38:39], v[0:1], off offset:112
	s_and_saveexec_b64 s[22:23], s[6:7]
	s_cbranch_execz .LBB0_303
	v_log_f32_e32 v2, v34
	v_ashrrev_i32_e32 v33, 31, v32
	v_lshl_add_u64 v[0:1], v[32:33], 2, s[80:81]
	v_ashrrev_i32_e32 v163, 31, v162
	v_lshl_add_u64 v[0:1], v[162:163], 2, v[0:1]
	v_lshl_add_u64 v[0:1], v[0:1], 0, v[184:185]
	v_add_f32_e32 v2, v229, v2
	global_store_dword v[0:1], v2, off
